# P6 (residual+rmsnorm phase) hand-rescheduled: gain vectors hoisted out of row loop, whole-row loads, next-row prefetch
# speedup vs baseline: 1.0156x; 1.0156x over previous
.LBB0_1034:
	s_or_b64 exec, exec, s[2:3]
	v_mov_b32_e32 v1, v208
	s_waitcnt lgkmcnt(0)
	s_barrier
	v_and_b32_e32 v3, 63, v208
	v_lshrrev_b32_e32 v4, 6, v208
	v_readlane_b32 s18, v252, 16
	v_readlane_b32 s19, v252, 17
	v_readlane_b32 s20, v252, 14
	v_readlane_b32 s21, v252, 15
	v_readlane_b32 s22, v252, 2
	v_readlane_b32 s23, v252, 3
	v_readfirstlane_b32 s2, v4
	v_lshlrev_b32_e32 v0, 4, v3
	v_lshlrev_b32_e32 v1, 5, v3
	v_lshlrev_b32_e32 v5, 3, v3
	v_lshlrev_b32_e32 v6, 2, v3
	v_add_u32_e32 v2, 0x1000, v1
	v_xor_b32_e32 v7, 0x80, v6
	v_xor_b32_e32 v8, 64, v6
	v_xor_b32_e32 v9, 32, v6
	v_xor_b32_e32 v10, 16, v6
	v_xor_b32_e32 v11, 8, v6
	v_xor_b32_e32 v204, 4, v6
	v_mov_b32_e32 v205, 0x358637bd
	v_mov_b32_e32 v214, 0
	v_mov_b32_e32 v215, 0
	s_add_i32 s2, s2, s74
	s_mov_b32 s3, s50
	s_add_u32 s20, s20, 0x2000
	s_addc_u32 s21, s21, 0
	s_add_u32 s24, s96, 0x20cc0000
	s_addc_u32 s25, s97, 0
	s_add_u32 s26, s96, 0x24ec0000
	s_addc_u32 s27, s97, 0
	s_cmp_ge_u32 s2, 0x2080
	s_cbranch_scc1 .Lp6_tail
	global_load_dwordx4 v[12:15], v1, s[18:19]
	global_load_dwordx4 v[16:19], v1, s[18:19] offset:16
	global_load_dwordx4 v[20:23], v1, s[18:19] offset:2048
	global_load_dwordx4 v[24:27], v1, s[18:19] offset:2064
	global_load_dwordx4 v[28:31], v2, s[18:19]
	global_load_dwordx4 v[32:35], v2, s[18:19] offset:16
	global_load_dwordx4 v[36:39], v2, s[18:19] offset:2048
	global_load_dwordx4 v[40:43], v2, s[18:19] offset:2064
	global_load_dwordx4 v[44:47], v1, s[20:21]
	global_load_dwordx4 v[48:51], v1, s[20:21] offset:16
	global_load_dwordx4 v[52:55], v1, s[20:21] offset:2048
	global_load_dwordx4 v[56:59], v1, s[20:21] offset:2064
	global_load_dwordx4 v[60:63], v2, s[20:21]
	global_load_dwordx4 v[64:67], v2, s[20:21] offset:16
	global_load_dwordx4 v[68:71], v2, s[20:21] offset:2048
	global_load_dwordx4 v[72:75], v2, s[20:21] offset:2064
	s_lshl_b32 s4, s2, 12
	s_add_u32 s6, s24, s4
	s_addc_u32 s7, s25, 0
	s_lshl_b32 s4, s2, 13
	s_cmp_lt_u32 s2, 0x2000
	s_cselect_b32 s8, s60, s62
	s_cselect_b32 s9, s61, s63
	s_cselect_b32 s28, 0, 0x4000000
	s_sub_u32 s4, s4, s28
	s_add_u32 s8, s8, s4
	s_addc_u32 s9, s9, 0
	global_load_dwordx4 v[76:79], v0, s[6:7]
	global_load_dwordx4 v[80:83], v0, s[6:7] offset:1024
	global_load_dwordx4 v[84:87], v0, s[6:7] offset:2048
	global_load_dwordx4 v[88:91], v0, s[6:7] offset:3072
	global_load_dwordx4 v[92:95], v1, s[8:9]
	global_load_dwordx4 v[96:99], v1, s[8:9] offset:16
	global_load_dwordx4 v[100:103], v1, s[8:9] offset:2048
	global_load_dwordx4 v[104:107], v1, s[8:9] offset:2064
	global_load_dwordx4 v[108:111], v2, s[8:9]
	global_load_dwordx4 v[112:115], v2, s[8:9] offset:16
	global_load_dwordx4 v[116:119], v2, s[8:9] offset:2048
	global_load_dwordx4 v[120:123], v2, s[8:9] offset:2064
	s_waitcnt vmcnt(0)
	s_branch .Lp6_A_go
.Lp6_A:
	s_waitcnt vmcnt(12)
.Lp6_A_go:
	s_add_u32 s29, s2, s3
	s_cmp_ge_u32 s29, 0x2080
	s_cbranch_scc1 .Lp6_A_nopf
	s_lshl_b32 s4, s29, 12
	s_add_u32 s6, s24, s4
	s_addc_u32 s7, s25, 0
	s_lshl_b32 s4, s29, 13
	s_cmp_lt_u32 s29, 0x2000
	s_cselect_b32 s8, s60, s62
	s_cselect_b32 s9, s61, s63
	s_cselect_b32 s28, 0, 0x4000000
	s_sub_u32 s4, s4, s28
	s_add_u32 s8, s8, s4
	s_addc_u32 s9, s9, 0
	global_load_dwordx4 v[124:127], v0, s[6:7]
	global_load_dwordx4 v[128:131], v0, s[6:7] offset:1024
	global_load_dwordx4 v[132:135], v0, s[6:7] offset:2048
	global_load_dwordx4 v[136:139], v0, s[6:7] offset:3072
	global_load_dwordx4 v[140:143], v1, s[8:9]
	global_load_dwordx4 v[144:147], v1, s[8:9] offset:16
	global_load_dwordx4 v[148:151], v1, s[8:9] offset:2048
	global_load_dwordx4 v[152:155], v1, s[8:9] offset:2064
	global_load_dwordx4 v[156:159], v2, s[8:9]
	global_load_dwordx4 v[160:163], v2, s[8:9] offset:16
	global_load_dwordx4 v[164:167], v2, s[8:9] offset:2048
	global_load_dwordx4 v[168:171], v2, s[8:9] offset:2064
.Lp6_A_nopf:
	s_lshl_b32 s4, s2, 12
	s_add_u32 s16, s26, s4
	s_addc_u32 s17, s27, 0
	s_lshl_b32 s4, s2, 13
	s_add_u32 s14, s22, s4
	s_addc_u32 s15, s23, 0
	v_lshlrev_b32_e32 v172, 16, v76
	v_and_b32_e32 v173, 0xffff0000, v76
	v_lshlrev_b32_e32 v174, 16, v77
	v_and_b32_e32 v175, 0xffff0000, v77
	v_lshlrev_b32_e32 v176, 16, v78
	v_and_b32_e32 v177, 0xffff0000, v78
	v_lshlrev_b32_e32 v178, 16, v79
	v_and_b32_e32 v179, 0xffff0000, v79
	v_lshlrev_b32_e32 v180, 16, v80
	v_and_b32_e32 v181, 0xffff0000, v80
	v_lshlrev_b32_e32 v182, 16, v81
	v_and_b32_e32 v183, 0xffff0000, v81
	v_lshlrev_b32_e32 v184, 16, v82
	v_and_b32_e32 v185, 0xffff0000, v82
	v_lshlrev_b32_e32 v186, 16, v83
	v_and_b32_e32 v187, 0xffff0000, v83
	v_lshlrev_b32_e32 v188, 16, v84
	v_and_b32_e32 v189, 0xffff0000, v84
	v_lshlrev_b32_e32 v190, 16, v85
	v_and_b32_e32 v191, 0xffff0000, v85
	v_lshlrev_b32_e32 v192, 16, v86
	v_and_b32_e32 v193, 0xffff0000, v86
	v_lshlrev_b32_e32 v194, 16, v87
	v_and_b32_e32 v195, 0xffff0000, v87
	v_lshlrev_b32_e32 v196, 16, v88
	v_and_b32_e32 v197, 0xffff0000, v88
	v_lshlrev_b32_e32 v198, 16, v89
	v_and_b32_e32 v199, 0xffff0000, v89
	v_lshlrev_b32_e32 v200, 16, v90
	v_and_b32_e32 v201, 0xffff0000, v90
	v_lshlrev_b32_e32 v202, 16, v91
	v_and_b32_e32 v203, 0xffff0000, v91
	v_mul_f32_e32 v206, v172, v172
	v_mul_f32_e32 v207, v173, v173
	v_mul_f32_e32 v210, v174, v174
	v_mul_f32_e32 v211, v175, v175
	v_fmac_f32_e32 v206, v176, v176
	v_fmac_f32_e32 v207, v177, v177
	v_fmac_f32_e32 v210, v178, v178
	v_fmac_f32_e32 v211, v179, v179
	v_fmac_f32_e32 v206, v180, v180
	v_fmac_f32_e32 v207, v181, v181
	v_fmac_f32_e32 v210, v182, v182
	v_fmac_f32_e32 v211, v183, v183
	v_fmac_f32_e32 v206, v184, v184
	v_fmac_f32_e32 v207, v185, v185
	v_fmac_f32_e32 v210, v186, v186
	v_fmac_f32_e32 v211, v187, v187
	v_fmac_f32_e32 v206, v188, v188
	v_fmac_f32_e32 v207, v189, v189
	v_fmac_f32_e32 v210, v190, v190
	v_fmac_f32_e32 v211, v191, v191
	v_fmac_f32_e32 v206, v192, v192
	v_fmac_f32_e32 v207, v193, v193
	v_fmac_f32_e32 v210, v194, v194
	v_fmac_f32_e32 v211, v195, v195
	v_fmac_f32_e32 v206, v196, v196
	v_fmac_f32_e32 v207, v197, v197
	v_fmac_f32_e32 v210, v198, v198
	v_fmac_f32_e32 v211, v199, v199
	v_fmac_f32_e32 v206, v200, v200
	v_fmac_f32_e32 v207, v201, v201
	v_fmac_f32_e32 v210, v202, v202
	v_fmac_f32_e32 v211, v203, v203
	v_add_f32_e32 v206, v206, v207
	v_add_f32_e32 v210, v210, v211
	v_add_f32_e32 v206, v206, v210
	ds_bpermute_b32 v212, v7, v206
	s_waitcnt lgkmcnt(0)
	v_add_f32_e32 v206, v206, v212
	ds_bpermute_b32 v212, v8, v206
	s_waitcnt lgkmcnt(0)
	v_add_f32_e32 v206, v206, v212
	ds_bpermute_b32 v212, v9, v206
	s_waitcnt lgkmcnt(0)
	v_add_f32_e32 v206, v206, v212
	ds_bpermute_b32 v212, v10, v206
	s_waitcnt lgkmcnt(0)
	v_add_f32_e32 v206, v206, v212
	ds_bpermute_b32 v212, v11, v206
	s_waitcnt lgkmcnt(0)
	v_add_f32_e32 v206, v206, v212
	ds_bpermute_b32 v212, v204, v206
	s_waitcnt lgkmcnt(0)
	v_add_f32_e32 v206, v206, v212
	v_fmamk_f32 v206, v206, 0x3a000000, v205
	v_rsq_f32_e32 v213, v206
	s_nop 0
	v_mul_f32_e32 v172, v172, v213
	v_fmac_f32_e32 v92, v172, v12
	v_mul_f32_e32 v173, v173, v213
	v_fmac_f32_e32 v93, v173, v13
	v_mul_f32_e32 v174, v174, v213
	v_fmac_f32_e32 v94, v174, v14
	v_mul_f32_e32 v175, v175, v213
	v_fmac_f32_e32 v95, v175, v15
	v_mul_f32_e32 v176, v176, v213
	v_fmac_f32_e32 v96, v176, v16
	v_mul_f32_e32 v177, v177, v213
	v_fmac_f32_e32 v97, v177, v17
	v_mul_f32_e32 v178, v178, v213
	v_fmac_f32_e32 v98, v178, v18
	v_mul_f32_e32 v179, v179, v213
	v_fmac_f32_e32 v99, v179, v19
	v_mul_f32_e32 v180, v180, v213
	v_fmac_f32_e32 v100, v180, v20
	v_mul_f32_e32 v181, v181, v213
	v_fmac_f32_e32 v101, v181, v21
	v_mul_f32_e32 v182, v182, v213
	v_fmac_f32_e32 v102, v182, v22
	v_mul_f32_e32 v183, v183, v213
	v_fmac_f32_e32 v103, v183, v23
	v_mul_f32_e32 v184, v184, v213
	v_fmac_f32_e32 v104, v184, v24
	v_mul_f32_e32 v185, v185, v213
	v_fmac_f32_e32 v105, v185, v25
	v_mul_f32_e32 v186, v186, v213
	v_fmac_f32_e32 v106, v186, v26
	v_mul_f32_e32 v187, v187, v213
	v_fmac_f32_e32 v107, v187, v27
	v_mul_f32_e32 v188, v188, v213
	v_fmac_f32_e32 v108, v188, v28
	v_mul_f32_e32 v189, v189, v213
	v_fmac_f32_e32 v109, v189, v29
	v_mul_f32_e32 v190, v190, v213
	v_fmac_f32_e32 v110, v190, v30
	v_mul_f32_e32 v191, v191, v213
	v_fmac_f32_e32 v111, v191, v31
	v_mul_f32_e32 v192, v192, v213
	v_fmac_f32_e32 v112, v192, v32
	v_mul_f32_e32 v193, v193, v213
	v_fmac_f32_e32 v113, v193, v33
	v_mul_f32_e32 v194, v194, v213
	v_fmac_f32_e32 v114, v194, v34
	v_mul_f32_e32 v195, v195, v213
	v_fmac_f32_e32 v115, v195, v35
	v_mul_f32_e32 v196, v196, v213
	v_fmac_f32_e32 v116, v196, v36
	v_mul_f32_e32 v197, v197, v213
	v_fmac_f32_e32 v117, v197, v37
	v_mul_f32_e32 v198, v198, v213
	v_fmac_f32_e32 v118, v198, v38
	v_mul_f32_e32 v199, v199, v213
	v_fmac_f32_e32 v119, v199, v39
	v_mul_f32_e32 v200, v200, v213
	v_fmac_f32_e32 v120, v200, v40
	v_mul_f32_e32 v201, v201, v213
	v_fmac_f32_e32 v121, v201, v41
	v_mul_f32_e32 v202, v202, v213
	v_fmac_f32_e32 v122, v202, v42
	v_mul_f32_e32 v203, v203, v213
	v_fmac_f32_e32 v123, v203, v43
	global_store_dwordx4 v1, v[92:95], s[14:15]
	global_store_dwordx4 v1, v[96:99], s[14:15] offset:16
	global_store_dwordx4 v1, v[100:103], s[14:15] offset:2048
	global_store_dwordx4 v1, v[104:107], s[14:15] offset:2064
	global_store_dwordx4 v2, v[108:111], s[14:15]
	global_store_dwordx4 v2, v[112:115], s[14:15] offset:16
	global_store_dwordx4 v2, v[116:119], s[14:15] offset:2048
	global_store_dwordx4 v2, v[120:123], s[14:15] offset:2064
	v_mul_f32_e32 v206, v92, v92
	v_mul_f32_e32 v207, v93, v93
	v_mul_f32_e32 v210, v94, v94
	v_mul_f32_e32 v211, v95, v95
	v_fmac_f32_e32 v206, v96, v96
	v_fmac_f32_e32 v207, v97, v97
	v_fmac_f32_e32 v210, v98, v98
	v_fmac_f32_e32 v211, v99, v99
	v_fmac_f32_e32 v206, v100, v100
	v_fmac_f32_e32 v207, v101, v101
	v_fmac_f32_e32 v210, v102, v102
	v_fmac_f32_e32 v211, v103, v103
	v_fmac_f32_e32 v206, v104, v104
	v_fmac_f32_e32 v207, v105, v105
	v_fmac_f32_e32 v210, v106, v106
	v_fmac_f32_e32 v211, v107, v107
	v_fmac_f32_e32 v206, v108, v108
	v_fmac_f32_e32 v207, v109, v109
	v_fmac_f32_e32 v210, v110, v110
	v_fmac_f32_e32 v211, v111, v111
	v_fmac_f32_e32 v206, v112, v112
	v_fmac_f32_e32 v207, v113, v113
	v_fmac_f32_e32 v210, v114, v114
	v_fmac_f32_e32 v211, v115, v115
	v_fmac_f32_e32 v206, v116, v116
	v_fmac_f32_e32 v207, v117, v117
	v_fmac_f32_e32 v210, v118, v118
	v_fmac_f32_e32 v211, v119, v119
	v_fmac_f32_e32 v206, v120, v120
	v_fmac_f32_e32 v207, v121, v121
	v_fmac_f32_e32 v210, v122, v122
	v_fmac_f32_e32 v211, v123, v123
	v_add_f32_e32 v206, v206, v207
	v_add_f32_e32 v210, v210, v211
	v_add_f32_e32 v206, v206, v210
	ds_bpermute_b32 v212, v7, v206
	s_waitcnt lgkmcnt(0)
	v_add_f32_e32 v206, v206, v212
	ds_bpermute_b32 v212, v8, v206
	s_waitcnt lgkmcnt(0)
	v_add_f32_e32 v206, v206, v212
	ds_bpermute_b32 v212, v9, v206
	s_waitcnt lgkmcnt(0)
	v_add_f32_e32 v206, v206, v212
	ds_bpermute_b32 v212, v10, v206
	s_waitcnt lgkmcnt(0)
	v_add_f32_e32 v206, v206, v212
	ds_bpermute_b32 v212, v11, v206
	s_waitcnt lgkmcnt(0)
	v_add_f32_e32 v206, v206, v212
	ds_bpermute_b32 v212, v204, v206
	s_waitcnt lgkmcnt(0)
	v_add_f32_e32 v206, v206, v212
	v_fmamk_f32 v206, v206, 0x3a000000, v205
	v_rsq_f32_e32 v213, v206
	s_nop 0
	v_mul_f32_e32 v172, v92, v213
	v_mul_f32_e32 v172, v172, v44
	v_mul_f32_e32 v173, v93, v213
	v_mul_f32_e32 v173, v173, v45
	v_mul_f32_e32 v174, v94, v213
	v_mul_f32_e32 v174, v174, v46
	v_mul_f32_e32 v175, v95, v213
	v_mul_f32_e32 v175, v175, v47
	v_mul_f32_e32 v176, v96, v213
	v_mul_f32_e32 v176, v176, v48
	v_mul_f32_e32 v177, v97, v213
	v_mul_f32_e32 v177, v177, v49
	v_mul_f32_e32 v178, v98, v213
	v_mul_f32_e32 v178, v178, v50
	v_mul_f32_e32 v179, v99, v213
	v_mul_f32_e32 v179, v179, v51
	v_mul_f32_e32 v180, v100, v213
	v_mul_f32_e32 v180, v180, v52
	v_mul_f32_e32 v181, v101, v213
	v_mul_f32_e32 v181, v181, v53
	v_mul_f32_e32 v182, v102, v213
	v_mul_f32_e32 v182, v182, v54
	v_mul_f32_e32 v183, v103, v213
	v_mul_f32_e32 v183, v183, v55
	v_mul_f32_e32 v184, v104, v213
	v_mul_f32_e32 v184, v184, v56
	v_mul_f32_e32 v185, v105, v213
	v_mul_f32_e32 v185, v185, v57
	v_mul_f32_e32 v186, v106, v213
	v_mul_f32_e32 v186, v186, v58
	v_mul_f32_e32 v187, v107, v213
	v_mul_f32_e32 v187, v187, v59
	v_mul_f32_e32 v188, v108, v213
	v_mul_f32_e32 v188, v188, v60
	v_mul_f32_e32 v189, v109, v213
	v_mul_f32_e32 v189, v189, v61
	v_mul_f32_e32 v190, v110, v213
	v_mul_f32_e32 v190, v190, v62
	v_mul_f32_e32 v191, v111, v213
	v_mul_f32_e32 v191, v191, v63
	v_mul_f32_e32 v192, v112, v213
	v_mul_f32_e32 v192, v192, v64
	v_mul_f32_e32 v193, v113, v213
	v_mul_f32_e32 v193, v193, v65
	v_mul_f32_e32 v194, v114, v213
	v_mul_f32_e32 v194, v194, v66
	v_mul_f32_e32 v195, v115, v213
	v_mul_f32_e32 v195, v195, v67
	v_mul_f32_e32 v196, v116, v213
	v_mul_f32_e32 v196, v196, v68
	v_mul_f32_e32 v197, v117, v213
	v_mul_f32_e32 v197, v197, v69
	v_mul_f32_e32 v198, v118, v213
	v_mul_f32_e32 v198, v198, v70
	v_mul_f32_e32 v199, v119, v213
	v_mul_f32_e32 v199, v199, v71
	v_mul_f32_e32 v200, v120, v213
	v_mul_f32_e32 v200, v200, v72
	v_mul_f32_e32 v201, v121, v213
	v_mul_f32_e32 v201, v201, v73
	v_mul_f32_e32 v202, v122, v213
	v_mul_f32_e32 v202, v202, v74
	v_mul_f32_e32 v203, v123, v213
	v_mul_f32_e32 v203, v203, v75
	v_cvt_pk_bf16_f32 v76, v172, v173
	v_cvt_pk_bf16_f32 v77, v174, v175
	v_cvt_pk_bf16_f32 v78, v176, v177
	v_cvt_pk_bf16_f32 v79, v178, v179
	v_cvt_pk_bf16_f32 v80, v180, v181
	v_cvt_pk_bf16_f32 v81, v182, v183
	v_cvt_pk_bf16_f32 v82, v184, v185
	v_cvt_pk_bf16_f32 v83, v186, v187
	v_cvt_pk_bf16_f32 v84, v188, v189
	v_cvt_pk_bf16_f32 v85, v190, v191
	v_cvt_pk_bf16_f32 v86, v192, v193
	v_cvt_pk_bf16_f32 v87, v194, v195
	v_cvt_pk_bf16_f32 v88, v196, v197
	v_cvt_pk_bf16_f32 v89, v198, v199
	v_cvt_pk_bf16_f32 v90, v200, v201
	v_cvt_pk_bf16_f32 v91, v202, v203
	global_store_dwordx4 v0, v[76:79], s[16:17]
	global_store_dwordx4 v0, v[80:83], s[16:17] offset:1024
	global_store_dwordx4 v0, v[84:87], s[16:17] offset:2048
	global_store_dwordx4 v0, v[88:91], s[16:17] offset:3072
	s_mov_b32 s2, s29
	s_cmp_ge_u32 s2, 0x2080
	s_cbranch_scc1 .Lp6_tail
.Lp6_B:
	s_waitcnt vmcnt(12)
	s_add_u32 s29, s2, s3
	s_cmp_ge_u32 s29, 0x2080
	s_cbranch_scc1 .Lp6_B_nopf
	s_lshl_b32 s4, s29, 12
	s_add_u32 s6, s24, s4
	s_addc_u32 s7, s25, 0
	s_lshl_b32 s4, s29, 13
	s_cmp_lt_u32 s29, 0x2000
	s_cselect_b32 s8, s60, s62
	s_cselect_b32 s9, s61, s63
	s_cselect_b32 s28, 0, 0x4000000
	s_sub_u32 s4, s4, s28
	s_add_u32 s8, s8, s4
	s_addc_u32 s9, s9, 0
	global_load_dwordx4 v[76:79], v0, s[6:7]
	global_load_dwordx4 v[80:83], v0, s[6:7] offset:1024
	global_load_dwordx4 v[84:87], v0, s[6:7] offset:2048
	global_load_dwordx4 v[88:91], v0, s[6:7] offset:3072
	global_load_dwordx4 v[92:95], v1, s[8:9]
	global_load_dwordx4 v[96:99], v1, s[8:9] offset:16
	global_load_dwordx4 v[100:103], v1, s[8:9] offset:2048
	global_load_dwordx4 v[104:107], v1, s[8:9] offset:2064
	global_load_dwordx4 v[108:111], v2, s[8:9]
	global_load_dwordx4 v[112:115], v2, s[8:9] offset:16
	global_load_dwordx4 v[116:119], v2, s[8:9] offset:2048
	global_load_dwordx4 v[120:123], v2, s[8:9] offset:2064
.Lp6_B_nopf:
	s_lshl_b32 s4, s2, 12
	s_add_u32 s16, s26, s4
	s_addc_u32 s17, s27, 0
	s_lshl_b32 s4, s2, 13
	s_add_u32 s14, s22, s4
	s_addc_u32 s15, s23, 0
	v_lshlrev_b32_e32 v172, 16, v124
	v_and_b32_e32 v173, 0xffff0000, v124
	v_lshlrev_b32_e32 v174, 16, v125
	v_and_b32_e32 v175, 0xffff0000, v125
	v_lshlrev_b32_e32 v176, 16, v126
	v_and_b32_e32 v177, 0xffff0000, v126
	v_lshlrev_b32_e32 v178, 16, v127
	v_and_b32_e32 v179, 0xffff0000, v127
	v_lshlrev_b32_e32 v180, 16, v128
	v_and_b32_e32 v181, 0xffff0000, v128
	v_lshlrev_b32_e32 v182, 16, v129
	v_and_b32_e32 v183, 0xffff0000, v129
	v_lshlrev_b32_e32 v184, 16, v130
	v_and_b32_e32 v185, 0xffff0000, v130
	v_lshlrev_b32_e32 v186, 16, v131
	v_and_b32_e32 v187, 0xffff0000, v131
	v_lshlrev_b32_e32 v188, 16, v132
	v_and_b32_e32 v189, 0xffff0000, v132
	v_lshlrev_b32_e32 v190, 16, v133
	v_and_b32_e32 v191, 0xffff0000, v133
	v_lshlrev_b32_e32 v192, 16, v134
	v_and_b32_e32 v193, 0xffff0000, v134
	v_lshlrev_b32_e32 v194, 16, v135
	v_and_b32_e32 v195, 0xffff0000, v135
	v_lshlrev_b32_e32 v196, 16, v136
	v_and_b32_e32 v197, 0xffff0000, v136
	v_lshlrev_b32_e32 v198, 16, v137
	v_and_b32_e32 v199, 0xffff0000, v137
	v_lshlrev_b32_e32 v200, 16, v138
	v_and_b32_e32 v201, 0xffff0000, v138
	v_lshlrev_b32_e32 v202, 16, v139
	v_and_b32_e32 v203, 0xffff0000, v139
	v_mul_f32_e32 v206, v172, v172
	v_mul_f32_e32 v207, v173, v173
	v_mul_f32_e32 v210, v174, v174
	v_mul_f32_e32 v211, v175, v175
	v_fmac_f32_e32 v206, v176, v176
	v_fmac_f32_e32 v207, v177, v177
	v_fmac_f32_e32 v210, v178, v178
	v_fmac_f32_e32 v211, v179, v179
	v_fmac_f32_e32 v206, v180, v180
	v_fmac_f32_e32 v207, v181, v181
	v_fmac_f32_e32 v210, v182, v182
	v_fmac_f32_e32 v211, v183, v183
	v_fmac_f32_e32 v206, v184, v184
	v_fmac_f32_e32 v207, v185, v185
	v_fmac_f32_e32 v210, v186, v186
	v_fmac_f32_e32 v211, v187, v187
	v_fmac_f32_e32 v206, v188, v188
	v_fmac_f32_e32 v207, v189, v189
	v_fmac_f32_e32 v210, v190, v190
	v_fmac_f32_e32 v211, v191, v191
	v_fmac_f32_e32 v206, v192, v192
	v_fmac_f32_e32 v207, v193, v193
	v_fmac_f32_e32 v210, v194, v194
	v_fmac_f32_e32 v211, v195, v195
	v_fmac_f32_e32 v206, v196, v196
	v_fmac_f32_e32 v207, v197, v197
	v_fmac_f32_e32 v210, v198, v198
	v_fmac_f32_e32 v211, v199, v199
	v_fmac_f32_e32 v206, v200, v200
	v_fmac_f32_e32 v207, v201, v201
	v_fmac_f32_e32 v210, v202, v202
	v_fmac_f32_e32 v211, v203, v203
	v_add_f32_e32 v206, v206, v207
	v_add_f32_e32 v210, v210, v211
	v_add_f32_e32 v206, v206, v210
	ds_bpermute_b32 v212, v7, v206
	s_waitcnt lgkmcnt(0)
	v_add_f32_e32 v206, v206, v212
	ds_bpermute_b32 v212, v8, v206
	s_waitcnt lgkmcnt(0)
	v_add_f32_e32 v206, v206, v212
	ds_bpermute_b32 v212, v9, v206
	s_waitcnt lgkmcnt(0)
	v_add_f32_e32 v206, v206, v212
	ds_bpermute_b32 v212, v10, v206
	s_waitcnt lgkmcnt(0)
	v_add_f32_e32 v206, v206, v212
	ds_bpermute_b32 v212, v11, v206
	s_waitcnt lgkmcnt(0)
	v_add_f32_e32 v206, v206, v212
	ds_bpermute_b32 v212, v204, v206
	s_waitcnt lgkmcnt(0)
	v_add_f32_e32 v206, v206, v212
	v_fmamk_f32 v206, v206, 0x3a000000, v205
	v_rsq_f32_e32 v213, v206
	s_nop 0
	v_mul_f32_e32 v172, v172, v213
	v_fmac_f32_e32 v140, v172, v12
	v_mul_f32_e32 v173, v173, v213
	v_fmac_f32_e32 v141, v173, v13
	v_mul_f32_e32 v174, v174, v213
	v_fmac_f32_e32 v142, v174, v14
	v_mul_f32_e32 v175, v175, v213
	v_fmac_f32_e32 v143, v175, v15
	v_mul_f32_e32 v176, v176, v213
	v_fmac_f32_e32 v144, v176, v16
	v_mul_f32_e32 v177, v177, v213
	v_fmac_f32_e32 v145, v177, v17
	v_mul_f32_e32 v178, v178, v213
	v_fmac_f32_e32 v146, v178, v18
	v_mul_f32_e32 v179, v179, v213
	v_fmac_f32_e32 v147, v179, v19
	v_mul_f32_e32 v180, v180, v213
	v_fmac_f32_e32 v148, v180, v20
	v_mul_f32_e32 v181, v181, v213
	v_fmac_f32_e32 v149, v181, v21
	v_mul_f32_e32 v182, v182, v213
	v_fmac_f32_e32 v150, v182, v22
	v_mul_f32_e32 v183, v183, v213
	v_fmac_f32_e32 v151, v183, v23
	v_mul_f32_e32 v184, v184, v213
	v_fmac_f32_e32 v152, v184, v24
	v_mul_f32_e32 v185, v185, v213
	v_fmac_f32_e32 v153, v185, v25
	v_mul_f32_e32 v186, v186, v213
	v_fmac_f32_e32 v154, v186, v26
	v_mul_f32_e32 v187, v187, v213
	v_fmac_f32_e32 v155, v187, v27
	v_mul_f32_e32 v188, v188, v213
	v_fmac_f32_e32 v156, v188, v28
	v_mul_f32_e32 v189, v189, v213
	v_fmac_f32_e32 v157, v189, v29
	v_mul_f32_e32 v190, v190, v213
	v_fmac_f32_e32 v158, v190, v30
	v_mul_f32_e32 v191, v191, v213
	v_fmac_f32_e32 v159, v191, v31
	v_mul_f32_e32 v192, v192, v213
	v_fmac_f32_e32 v160, v192, v32
	v_mul_f32_e32 v193, v193, v213
	v_fmac_f32_e32 v161, v193, v33
	v_mul_f32_e32 v194, v194, v213
	v_fmac_f32_e32 v162, v194, v34
	v_mul_f32_e32 v195, v195, v213
	v_fmac_f32_e32 v163, v195, v35
	v_mul_f32_e32 v196, v196, v213
	v_fmac_f32_e32 v164, v196, v36
	v_mul_f32_e32 v197, v197, v213
	v_fmac_f32_e32 v165, v197, v37
	v_mul_f32_e32 v198, v198, v213
	v_fmac_f32_e32 v166, v198, v38
	v_mul_f32_e32 v199, v199, v213
	v_fmac_f32_e32 v167, v199, v39
	v_mul_f32_e32 v200, v200, v213
	v_fmac_f32_e32 v168, v200, v40
	v_mul_f32_e32 v201, v201, v213
	v_fmac_f32_e32 v169, v201, v41
	v_mul_f32_e32 v202, v202, v213
	v_fmac_f32_e32 v170, v202, v42
	v_mul_f32_e32 v203, v203, v213
	v_fmac_f32_e32 v171, v203, v43
	global_store_dwordx4 v1, v[140:143], s[14:15]
	global_store_dwordx4 v1, v[144:147], s[14:15] offset:16
	global_store_dwordx4 v1, v[148:151], s[14:15] offset:2048
	global_store_dwordx4 v1, v[152:155], s[14:15] offset:2064
	global_store_dwordx4 v2, v[156:159], s[14:15]
	global_store_dwordx4 v2, v[160:163], s[14:15] offset:16
	global_store_dwordx4 v2, v[164:167], s[14:15] offset:2048
	global_store_dwordx4 v2, v[168:171], s[14:15] offset:2064
	v_mul_f32_e32 v206, v140, v140
	v_mul_f32_e32 v207, v141, v141
	v_mul_f32_e32 v210, v142, v142
	v_mul_f32_e32 v211, v143, v143
	v_fmac_f32_e32 v206, v144, v144
	v_fmac_f32_e32 v207, v145, v145
	v_fmac_f32_e32 v210, v146, v146
	v_fmac_f32_e32 v211, v147, v147
	v_fmac_f32_e32 v206, v148, v148
	v_fmac_f32_e32 v207, v149, v149
	v_fmac_f32_e32 v210, v150, v150
	v_fmac_f32_e32 v211, v151, v151
	v_fmac_f32_e32 v206, v152, v152
	v_fmac_f32_e32 v207, v153, v153
	v_fmac_f32_e32 v210, v154, v154
	v_fmac_f32_e32 v211, v155, v155
	v_fmac_f32_e32 v206, v156, v156
	v_fmac_f32_e32 v207, v157, v157
	v_fmac_f32_e32 v210, v158, v158
	v_fmac_f32_e32 v211, v159, v159
	v_fmac_f32_e32 v206, v160, v160
	v_fmac_f32_e32 v207, v161, v161
	v_fmac_f32_e32 v210, v162, v162
	v_fmac_f32_e32 v211, v163, v163
	v_fmac_f32_e32 v206, v164, v164
	v_fmac_f32_e32 v207, v165, v165
	v_fmac_f32_e32 v210, v166, v166
	v_fmac_f32_e32 v211, v167, v167
	v_fmac_f32_e32 v206, v168, v168
	v_fmac_f32_e32 v207, v169, v169
	v_fmac_f32_e32 v210, v170, v170
	v_fmac_f32_e32 v211, v171, v171
	v_add_f32_e32 v206, v206, v207
	v_add_f32_e32 v210, v210, v211
	v_add_f32_e32 v206, v206, v210
	ds_bpermute_b32 v212, v7, v206
	s_waitcnt lgkmcnt(0)
	v_add_f32_e32 v206, v206, v212
	ds_bpermute_b32 v212, v8, v206
	s_waitcnt lgkmcnt(0)
	v_add_f32_e32 v206, v206, v212
	ds_bpermute_b32 v212, v9, v206
	s_waitcnt lgkmcnt(0)
	v_add_f32_e32 v206, v206, v212
	ds_bpermute_b32 v212, v10, v206
	s_waitcnt lgkmcnt(0)
	v_add_f32_e32 v206, v206, v212
	ds_bpermute_b32 v212, v11, v206
	s_waitcnt lgkmcnt(0)
	v_add_f32_e32 v206, v206, v212
	ds_bpermute_b32 v212, v204, v206
	s_waitcnt lgkmcnt(0)
	v_add_f32_e32 v206, v206, v212
	v_fmamk_f32 v206, v206, 0x3a000000, v205
	v_rsq_f32_e32 v213, v206
	s_nop 0
	v_mul_f32_e32 v172, v140, v213
	v_mul_f32_e32 v172, v172, v44
	v_mul_f32_e32 v173, v141, v213
	v_mul_f32_e32 v173, v173, v45
	v_mul_f32_e32 v174, v142, v213
	v_mul_f32_e32 v174, v174, v46
	v_mul_f32_e32 v175, v143, v213
	v_mul_f32_e32 v175, v175, v47
	v_mul_f32_e32 v176, v144, v213
	v_mul_f32_e32 v176, v176, v48
	v_mul_f32_e32 v177, v145, v213
	v_mul_f32_e32 v177, v177, v49
	v_mul_f32_e32 v178, v146, v213
	v_mul_f32_e32 v178, v178, v50
	v_mul_f32_e32 v179, v147, v213
	v_mul_f32_e32 v179, v179, v51
	v_mul_f32_e32 v180, v148, v213
	v_mul_f32_e32 v180, v180, v52
	v_mul_f32_e32 v181, v149, v213
	v_mul_f32_e32 v181, v181, v53
	v_mul_f32_e32 v182, v150, v213
	v_mul_f32_e32 v182, v182, v54
	v_mul_f32_e32 v183, v151, v213
	v_mul_f32_e32 v183, v183, v55
	v_mul_f32_e32 v184, v152, v213
	v_mul_f32_e32 v184, v184, v56
	v_mul_f32_e32 v185, v153, v213
	v_mul_f32_e32 v185, v185, v57
	v_mul_f32_e32 v186, v154, v213
	v_mul_f32_e32 v186, v186, v58
	v_mul_f32_e32 v187, v155, v213
	v_mul_f32_e32 v187, v187, v59
	v_mul_f32_e32 v188, v156, v213
	v_mul_f32_e32 v188, v188, v60
	v_mul_f32_e32 v189, v157, v213
	v_mul_f32_e32 v189, v189, v61
	v_mul_f32_e32 v190, v158, v213
	v_mul_f32_e32 v190, v190, v62
	v_mul_f32_e32 v191, v159, v213
	v_mul_f32_e32 v191, v191, v63
	v_mul_f32_e32 v192, v160, v213
	v_mul_f32_e32 v192, v192, v64
	v_mul_f32_e32 v193, v161, v213
	v_mul_f32_e32 v193, v193, v65
	v_mul_f32_e32 v194, v162, v213
	v_mul_f32_e32 v194, v194, v66
	v_mul_f32_e32 v195, v163, v213
	v_mul_f32_e32 v195, v195, v67
	v_mul_f32_e32 v196, v164, v213
	v_mul_f32_e32 v196, v196, v68
	v_mul_f32_e32 v197, v165, v213
	v_mul_f32_e32 v197, v197, v69
	v_mul_f32_e32 v198, v166, v213
	v_mul_f32_e32 v198, v198, v70
	v_mul_f32_e32 v199, v167, v213
	v_mul_f32_e32 v199, v199, v71
	v_mul_f32_e32 v200, v168, v213
	v_mul_f32_e32 v200, v200, v72
	v_mul_f32_e32 v201, v169, v213
	v_mul_f32_e32 v201, v201, v73
	v_mul_f32_e32 v202, v170, v213
	v_mul_f32_e32 v202, v202, v74
	v_mul_f32_e32 v203, v171, v213
	v_mul_f32_e32 v203, v203, v75
	v_cvt_pk_bf16_f32 v124, v172, v173
	v_cvt_pk_bf16_f32 v125, v174, v175
	v_cvt_pk_bf16_f32 v126, v176, v177
	v_cvt_pk_bf16_f32 v127, v178, v179
	v_cvt_pk_bf16_f32 v128, v180, v181
	v_cvt_pk_bf16_f32 v129, v182, v183
	v_cvt_pk_bf16_f32 v130, v184, v185
	v_cvt_pk_bf16_f32 v131, v186, v187
	v_cvt_pk_bf16_f32 v132, v188, v189
	v_cvt_pk_bf16_f32 v133, v190, v191
	v_cvt_pk_bf16_f32 v134, v192, v193
	v_cvt_pk_bf16_f32 v135, v194, v195
	v_cvt_pk_bf16_f32 v136, v196, v197
	v_cvt_pk_bf16_f32 v137, v198, v199
	v_cvt_pk_bf16_f32 v138, v200, v201
	v_cvt_pk_bf16_f32 v139, v202, v203
	global_store_dwordx4 v0, v[124:127], s[16:17]
	global_store_dwordx4 v0, v[128:131], s[16:17] offset:1024
	global_store_dwordx4 v0, v[132:135], s[16:17] offset:2048
	global_store_dwordx4 v0, v[136:139], s[16:17] offset:3072
	s_mov_b32 s2, s29
	s_cmp_ge_u32 s2, 0x2080
	s_cbranch_scc0 .Lp6_A
.Lp6_tail:
	s_cmp_ge_u32 s2, 0x2100
	s_cbranch_scc1 .Lp6_done
	s_lshl_b32 s4, s2, 12
	s_add_u32 s16, s26, s4
	s_addc_u32 s17, s27, 0
	global_store_dwordx2 v5, v[214:215], s[16:17]
	global_store_dwordx2 v5, v[214:215], s[16:17] offset:512
	global_store_dwordx2 v5, v[214:215], s[16:17] offset:1024
	global_store_dwordx2 v5, v[214:215], s[16:17] offset:1536
	global_store_dwordx2 v5, v[214:215], s[16:17] offset:2048
	global_store_dwordx2 v5, v[214:215], s[16:17] offset:2560
	global_store_dwordx2 v5, v[214:215], s[16:17] offset:3072
	global_store_dwordx2 v5, v[214:215], s[16:17] offset:3584
	s_add_u32 s2, s2, s3
	s_branch .Lp6_tail
.Lp6_done:
	v_readlane_b32 s75, v252, 46
	s_waitcnt vmcnt(0)
	v_mov_b32_e32 v0, v208
	s_barrier
	s_nop 0
	v_cmp_eq_u32_e32 vcc, 0, v0
	s_and_saveexec_b64 s[2:3], vcc
	s_cbranch_execz .LBB0_1094
	s_add_i32 s5, 0, 0x21ff0
	v_mov_b32_e32 v0, s5
	s_getreg_b32 s4, hwreg(HW_REG_XCC_ID, 0, 4)
	s_waitcnt vmcnt(0) expcnt(0) lgkmcnt(0)
	ds_read_b32 v2, v0
	s_add_i32 s5, 0, 0x21ff4
	v_mov_b32_e32 v0, s5
	ds_read_b32 v0, v0
	s_and_b32 s33, s4, 15
	s_waitcnt lgkmcnt(1)
	v_cmp_ne_u32_e32 vcc, 0, v2
	s_cbranch_vccnz .LBB0_1058
	s_add_u32 s4, s96, 0x352b8a00
	s_addc_u32 s5, s97, 0
	s_add_u32 s6, s96, 0x352b8c00
	s_addc_u32 s7, s97, 0
	s_add_u32 s8, s96, 0x352b8d00
	s_addc_u32 s9, s97, 0
	s_add_u32 s14, s96, 0x352b8e00
	s_addc_u32 s15, s97, 0
	s_add_u32 s16, s96, 0x352b8f00
	s_addc_u32 s17, s97, 0
	s_add_u32 s18, s96, 0x352b9000
	s_addc_u32 s19, s97, 0
	s_add_u32 s20, s96, 0x352b9100
	s_addc_u32 s21, s97, 0
	s_add_u32 s22, s96, 0x352b9200
	s_addc_u32 s23, s97, 0
	s_add_u32 s24, s96, 0x352b9300
	s_addc_u32 s25, s97, 0
	s_add_u32 s26, s96, 0x352b9400
	s_addc_u32 s27, s97, 0
	s_add_u32 s28, s96, 0x352b9500
	s_addc_u32 s29, s97, 0
	s_add_u32 s30, s96, 0x352b9600
	s_addc_u32 s31, s97, 0
	s_add_u32 s34, s96, 0x352b9700
	s_addc_u32 s35, s97, 0
	s_add_u32 s36, s96, 0x352b9800
	s_addc_u32 s37, s97, 0
	s_add_u32 s38, s96, 0x352b9900
	s_addc_u32 s39, s97, 0
	s_add_u32 s40, s96, 0x352b9a00
	s_addc_u32 s41, s97, 0
	s_add_u32 s42, s96, 0x352b9b00
	s_addc_u32 s43, s97, 0
	s_mov_b32 s51, 1
	v_mov_b32_e32 v16, 0
	s_branch .LBB0_1046
